# attention: K tiles triple-buffered in LDS (rotating address registers), first K fragment pair of the next tile prefetched before the tile barrier; packed P half in place
# baseline (speedup 1.0000x reference)
; #define SBAR() __builtin_amdgcn_sched_barrier(0)
; #define SLOAD(i, k0) do { sr_[i].vs0 = LD8(&Vh[(long)((k0) + sr) * LDK + sc]); sr_[i].vs1 = LD8(&Vh[(long)((k0) + 32 + sr) * LDK + sc]); \
;     sr_[i].ks0 = LD8(&Kh[(long)((k0) + sr) * LDK + sc]); sr_[i].ks1 = LD8(&Kh[(long)((k0) + 32 + sr) * LDK + sc]); } while (0)
; #define SWAIT() asm volatile("s_waitcnt vmcnt(4)" ::: "memory")
; __device__ __forceinline__ void finishSM(f32x16& p0, f32x16& p1, float alpha, float& l_reg, bf16x8& pa0, bf16x8& pa1, bf16x8& pa2, bf16x8& pa3) {
;     for (int r = 0; r < 16; ++r) p1[r] = __builtin_amdgcn_exp2f(p1[r]);
;     float ps = 0; for (int r = 0; r < 16; ++r) ps += p0[r]; for (int r = 0; r < 16; ++r) ps += p1[r];
;     { auto rr = __builtin_amdgcn_permlane32_swap(__float_as_uint(ps), __float_as_uint(ps), false, false);
;       ps = __uint_as_float(rr[0]) + __uint_as_float(rr[1]); }
;     l_reg = l_reg * alpha + ps;
;     ...
;     PK4(p0, 0, pa0); PK4(p0, 8, pa1); PK4(p1, 0, pa2); PK4(p1, 8, pa3);
;     ...
; }
; __device__ __forceinline__ void qkt(f32x16& p0, f32x16& p1, const bf16_t* Ks, const bf16x8* qr, int r32, int hi) {
;     p0 = f32x16{}; p1 = f32x16{};
;     for (int d0 = 0; d0 < 8; ++d0) { int cb = (d0 * 16 + hi * 8) * 2;
;         bf16x8 b0 = *reinterpret_cast<const bf16x8*>((const char*)Ks + KSWZ(r32, cb));
;         bf16x8 b1 = *reinterpret_cast<const bf16x8*>((const char*)Ks + KSWZ(32 + r32, cb));
;         p0 = __builtin_amdgcn_mfma_f32_32x32x16_bf16(b0, qr[d0], p0, 0, 0, 0);
;         p1 = __builtin_amdgcn_mfma_f32_32x32x16_bf16(b1, qr[d0], p1, 0, 0, 0); }
; }
; __device__ __forceinline__ void attn_body(const bf16_t* __restrict__ Qb, const bf16_t* __restrict__ Kh, const bf16_t* __restrict__ Vh, const bf16_t* __restrict__ Zb, ...
;     ...
;     f32x16 pA0, pA1, pB0, pB1; bf16x8 pa0, pa1, pa2, pa3; const int NT = seq / KVBLK;
;     constexpr int SE = 0, SO = 1;
;     asm volatile("s_waitcnt vmcnt(0)" ::: "memory"); SWRITE(0, SE); __syncthreads();
;     qkt(pA0, pA1, K_lds, qr, r32, hi); partialSM(pA0, pA1, negBC);
;     SLOAD(SE, 2 * KVBLK);
;     SWAIT(); SWRITE(1, SO); __syncthreads();
;     if (__builtin_amdgcn_readfirstlane(tid) >= 256) __builtin_amdgcn_s_setprio(1);
;     for (int j = 1; j + 1 < NT; j += 2) {
;         SBAR(); qkt(pB0, pB1, (bf16_t*)((char*)K_lds + SHM_K), qr, r32, hi);
.LBB0_489:
	v_and_b32_e32 v203, 63, v200
	v_exp_f32_e32 v235, v1
	v_lshlrev_b32_e32 v1, 4, v203
	v_exp_f32_e32 v233, v0
	v_exp_f32_e32 v231, v2
	v_lshlrev_b32_e32 v0, 3, v203
	v_and_b32_e32 v1, 0xc0, v1
	v_lshlrev_b32_e32 v2, 1, v203
	v_and_or_b32 v1, v0, 24, v1
	v_and_b32_e32 v2, 32, v2
	v_and_b32_e32 v0, 0x100, v0
	s_cmp_lg_u32 0, -1
	v_or3_b32 v0, v1, v2, v0
	s_cselect_b32 s42, 0, 0
	s_mov_b32 s23, s9
	v_add_u32_e32 v206, s42, v0
	s_addk_i32 s42, 0x4000
	v_add_u32_e32 v205, s42, v0
	v_lshl_add_u64 v[0:1], v[186:187], 0, s[22:23]
	v_exp_f32_e32 v234, v3
	v_exp_f32_e32 v230, v4
	v_exp_f32_e32 v232, v5
	v_exp_f32_e32 v228, v6
	v_exp_f32_e32 v229, v7
	v_exp_f32_e32 v225, v8
	v_exp_f32_e32 v227, v9
	v_exp_f32_e32 v224, v10
	v_exp_f32_e32 v226, v11
	v_exp_f32_e32 v221, v12
	v_exp_f32_e32 v223, v13
	v_exp_f32_e32 v181, v14
	v_exp_f32_e32 v222, v15
	v_mad_u64_u32 v[2:3], s[22:23], v0, s30, 0
	v_and_b32_e32 v0, 15, v200
	v_lshlrev_b32_e32 v0, 4, v0
	v_mad_i32_i24 v1, v1, s30, v3
	v_or3_b32 v0, v2, s41, v0
	v_mov_b32_e32 v204, 0
	s_mov_b32 s39, 4
	s_add_i32 s40, s33, -1
	v_lshl_add_u64 v[190:191], s[12:13], 0, v[0:1]
	v_mov_b32_e32 v0, 0
	v_mov_b32_e32 v1, v204
	v_mov_b32_e32 v2, v204
	v_mov_b32_e32 v3, v204
	v_mov_b32_e32 v4, v204
	v_mov_b32_e32 v5, v204
	v_mov_b32_e32 v6, v204
	v_mov_b32_e32 v7, v204
	v_mov_b32_e32 v8, v204
	v_mov_b32_e32 v9, v204
	v_mov_b32_e32 v10, v204
	v_mov_b32_e32 v11, v204
	v_mov_b32_e32 v12, v204
	v_mov_b32_e32 v13, v204
	v_mov_b32_e32 v14, v204
	v_mov_b32_e32 v15, v204
	v_mov_b32_e32 v16, 0
	v_mov_b32_e32 v17, v204
	v_mov_b32_e32 v18, v204
	v_mov_b32_e32 v19, v204
	v_mov_b32_e32 v20, v204
	v_mov_b32_e32 v21, v204
	v_mov_b32_e32 v22, v204
	v_mov_b32_e32 v23, v204
	v_mov_b32_e32 v24, v204
	v_mov_b32_e32 v25, v204
	v_mov_b32_e32 v26, v204
	v_mov_b32_e32 v27, v204
	v_mov_b32_e32 v28, v204
	v_mov_b32_e32 v29, v204
	v_mov_b32_e32 v30, v204
	v_mov_b32_e32 v31, v204
	v_mov_b32_e32 v32, 0
	v_mov_b32_e32 v33, v204
	v_mov_b32_e32 v34, v204
	v_mov_b32_e32 v35, v204
	v_mov_b32_e32 v36, v204
	v_mov_b32_e32 v37, v204
	v_mov_b32_e32 v38, v204
	v_mov_b32_e32 v39, v204
	v_mov_b32_e32 v40, v204
	v_mov_b32_e32 v41, v204
	v_mov_b32_e32 v42, v204
	v_mov_b32_e32 v43, v204
	v_mov_b32_e32 v44, v204
	v_mov_b32_e32 v45, v204
	v_mov_b32_e32 v46, v204
	v_mov_b32_e32 v47, v204
	v_mov_b32_e32 v48, 0
	v_mov_b32_e32 v49, v204
	v_mov_b32_e32 v50, v204
	v_mov_b32_e32 v51, v204
	v_mov_b32_e32 v52, v204
	v_mov_b32_e32 v53, v204
	v_mov_b32_e32 v54, v204
	v_mov_b32_e32 v55, v204
	v_mov_b32_e32 v56, v204
	v_mov_b32_e32 v57, v204
	v_mov_b32_e32 v58, v204
	v_mov_b32_e32 v59, v204
	v_mov_b32_e32 v60, v204
	v_mov_b32_e32 v61, v204
	v_mov_b32_e32 v62, v204
	v_mov_b32_e32 v63, v204
	v_exp_f32_e32 v64, v64
	v_exp_f32_e32 v65, v65
	v_exp_f32_e32 v66, v66
	v_exp_f32_e32 v67, v67
	v_exp_f32_e32 v68, v68
	v_exp_f32_e32 v69, v69
	v_exp_f32_e32 v70, v70
	v_exp_f32_e32 v71, v71
	v_exp_f32_e32 v72, v72
	v_exp_f32_e32 v73, v73
	v_exp_f32_e32 v74, v74
	v_exp_f32_e32 v75, v75
	v_exp_f32_e32 v76, v76
	v_exp_f32_e32 v77, v77
	v_exp_f32_e32 v78, v78
	v_exp_f32_e32 v79, v79
	s_mov_b32 s100, 0xfffa0000
	s_mov_b32 s101, -1
	s_mov_b32 s98, 0xfffd0000
	s_mov_b32 s99, -1
	v_add_u32_e32 v252, 0x14000, v207
	v_add_u32_e32 v253, 0x14000, v208
	v_lshl_add_u64 v[190:191], v[190:191], 0, s[100:101]
	s_mov_b32 s100, 0x60000
	s_mov_b32 s101, 0
	v_add_u32_e32 v209, 0x14000, v209
	v_add_u32_e32 v210, 0x14000, v210
	v_add_u32_e32 v211, 0xc000, v211
	v_add_u32_e32 v212, 0xc000, v212
	v_add_u32_e32 v213, 0xc000, v213
	v_add_u32_e32 v214, 0xc000, v214
	v_add_u32_e32 v215, 0xc000, v215
	v_add_u32_e32 v216, 0xc000, v216
	v_add_u32_e32 v217, 0xc000, v217
	v_add_u32_e32 v218, 0xc000, v218
	s_waitcnt vmcnt(0)
	ds_write_b128 v209, v[148:151]
	ds_write_b128 v210, v[152:155]
	v_add_u32_e32 v209, 0xffff4000, v209
	v_add_u32_e32 v210, 0xffff4000, v210
	s_mov_b32 s14, 1
	v_lshl_add_u64 v[152:153], v[190:191], 0, s[100:101]
	v_lshl_add_u64 v[148:149], v[152:153], 0, s[98:99]
	global_load_dwordx4 v[152:155], v[152:153], off offset:-512
	global_load_dwordx4 v[148:151], v[148:149], off offset:-512
	s_waitcnt lgkmcnt(0)
	s_barrier
	ds_read_b128 v[168:171], v211
	ds_read_b128 v[172:175], v211 offset:8192
.LBB0_490:
	ds_read_b128 v[236:239], v212
	ds_read_b128 v[240:243], v212 offset:8192
	ds_read_b128 v[244:247], v213
	ds_read_b128 v[248:251], v213 offset:8192
	v_add_f32_e32 v219, v233, v235
	v_cvt_pk_bf16_f32 v160, v233, v235
	s_waitcnt lgkmcnt(5)
	v_mfma_f32_32x32x16_bf16 v[96:111], v[168:171], v[116:119], 0
	v_add_f32_e32 v219, v231, v219
	v_cvt_pk_bf16_f32 v161, v231, v234
	v_add_f32_e32 v219, v234, v219
	v_cvt_pk_bf16_f32 v162, v230, v232
	v_add_f32_e32 v219, v230, v219
	s_waitcnt lgkmcnt(4)
	v_mfma_f32_32x32x16_bf16 v[80:95], v[172:175], v[116:119], 0
	v_cvt_pk_bf16_f32 v163, v228, v229
	v_add_f32_e32 v219, v232, v219
	v_cvt_pk_bf16_f32 v164, v225, v227
	v_add_f32_e32 v219, v228, v219
	v_cvt_pk_bf16_f32 v165, v224, v226
	s_waitcnt lgkmcnt(3)
	v_mfma_f32_32x32x16_bf16 v[96:111], v[236:239], v[124:127], v[96:111]
	v_add_f32_e32 v219, v229, v219
	v_cvt_pk_bf16_f32 v166, v221, v223
	v_add_f32_e32 v219, v225, v219
	v_cvt_pk_bf16_f32 v167, v181, v222
	v_add_f32_e32 v219, v227, v219
	s_waitcnt lgkmcnt(2)
	v_mfma_f32_32x32x16_bf16 v[80:95], v[240:243], v[124:127], v[80:95]
	ds_read_b128 v[236:239], v214
	ds_read_b128 v[240:243], v214 offset:8192
	v_permlane32_swap_b32_e32 v160, v162
	v_add_f32_e32 v219, v224, v219
	s_waitcnt lgkmcnt(3)
	v_mfma_f32_32x32x16_bf16 v[96:111], v[244:247], v[112:115], v[96:111]
	v_permlane32_swap_b32_e32 v161, v163
	v_add_f32_e32 v219, v226, v219
	v_permlane32_swap_b32_e32 v164, v166
	s_waitcnt lgkmcnt(2)
; __device__ __forceinline__ void finishSM(f32x16& p0, f32x16& p1, float alpha, float& l_reg, bf16x8& pa0, bf16x8& pa1, bf16x8& pa2, bf16x8& pa3) {
;     for (int r = 0; r < 16; ++r) p1[r] = __builtin_amdgcn_exp2f(p1[r]);
;     float ps = 0; for (int r = 0; r < 16; ++r) ps += p0[r]; for (int r = 0; r < 16; ++r) ps += p1[r];
;     { auto rr = __builtin_amdgcn_permlane32_swap(__float_as_uint(ps), __float_as_uint(ps), false, false);
;       ps = __uint_as_float(rr[0]) + __uint_as_float(rr[1]); }
;     l_reg = l_reg * alpha + ps;
;     ...
;     PK4(p0, 0, pa0); PK4(p0, 8, pa1); PK4(p1, 0, pa2); PK4(p1, 8, pa3);
;     ...
; }
; __device__ __forceinline__ void qkt(f32x16& p0, f32x16& p1, const bf16_t* Ks, const bf16x8* qr, int r32, int hi) {
;     p0 = f32x16{}; p1 = f32x16{};
;     for (int d0 = 0; d0 < 8; ++d0) { int cb = (d0 * 16 + hi * 8) * 2;
;         bf16x8 b0 = *reinterpret_cast<const bf16x8*>((const char*)Ks + KSWZ(r32, cb));
;         bf16x8 b1 = *reinterpret_cast<const bf16x8*>((const char*)Ks + KSWZ(32 + r32, cb));
;         p0 = __builtin_amdgcn_mfma_f32_32x32x16_bf16(b0, qr[d0], p0, 0, 0, 0);
;         p1 = __builtin_amdgcn_mfma_f32_32x32x16_bf16(b1, qr[d0], p1, 0, 0, 0); }
; }
; __device__ __forceinline__ int v_st(int k, int c) { const int kk = (k & ~0xC) | ((k & 4) << 1) | ((k & 8) >> 1); return ((kk >> 3) * 4 + (c >> 5)) * 512 + ((kk & 7) * 32 + (c & 31)) * 2; }
; __device__ __forceinline__ int v_rd_base(int lane) { return ((lane & 3) << 3) | (((lane >> 2) & 3) << 6) | (((lane >> 4) & 1) << 5) | (((lane >> 5) & 1) << 8); }
; template <int OFF> __device__ __forceinline__ s16x4 tr_read(int vb) {
;     s16x4 r; asm volatile("ds_read_b64_tr_b16 %0, %1 offset:%2" : "=&v"(r) : "v"(vb), "i"(OFF) : "memory"); return r;
; }
; template <int D0> __device__ __forceinline__ void pv_one(f32x16& od, int vb, bf16x8 pa0, bf16x8 pa1, bf16x8 pa2, bf16x8 pa3) {
; __device__ __forceinline__ void attn_body(const bf16_t* __restrict__ Qb, const bf16_t* __restrict__ Kh, const bf16_t* __restrict__ Vh, const bf16_t* __restrict__ Zb, ...
;     ...
;         SBAR(); qkt(pA0, pA1, K_lds, qr, r32, hi);
;         finishSM(pB0, pB1, 1.f, l_reg, pa0, pa1, pa2, pa3); SBAR();
;         SLOAD(SE, ((j + 3 < NT) ? (j + 3) : (NT - 1)) * KVBLK); SBAR();
;         pv_d0(o, vb0 + (int)SHM_V, pa0, pa1, pa2, pa3); partialSM(pA0, pA1, negBC);
;         __syncthreads(); SWAIT(); SWRITE(1, SO);
	v_mfma_f32_32x32x16_bf16 v[80:95], v[248:251], v[112:115], v[80:95]
	ds_read_b128 v[244:247], v215
	ds_read_b128 v[248:251], v215 offset:8192
	v_add_f32_e32 v219, v221, v219
	v_permlane32_swap_b32_e32 v165, v167
	v_add_f32_e32 v219, v223, v219
	s_waitcnt lgkmcnt(3)
	v_mfma_f32_32x32x16_bf16 v[96:111], v[236:239], v[120:123], v[96:111]
	v_add_f32_e32 v219, v181, v219
	v_add_f32_e32 v219, v222, v219
	v_add_f32_e32 v219, v64, v219
	v_cvt_pk_bf16_f32 v64, v64, v65
	s_waitcnt lgkmcnt(2)
	v_mfma_f32_32x32x16_bf16 v[80:95], v[240:243], v[120:123], v[80:95]
	ds_read_b128 v[236:239], v216
	ds_read_b128 v[240:243], v216 offset:8192
	v_add_f32_e32 v219, v65, v219
	v_cvt_pk_bf16_f32 v65, v66, v67
	v_add_f32_e32 v219, v66, v219
	v_cvt_pk_bf16_f32 v66, v68, v69
	s_waitcnt lgkmcnt(3)
	v_mfma_f32_32x32x16_bf16 v[96:111], v[244:247], v[132:135], v[96:111]
	v_add_f32_e32 v219, v67, v219
	v_cvt_pk_bf16_f32 v67, v70, v71
	v_add_f32_e32 v219, v68, v219
	v_cvt_pk_bf16_f32 v68, v72, v73
	s_waitcnt lgkmcnt(2)
	v_mfma_f32_32x32x16_bf16 v[80:95], v[248:251], v[132:135], v[80:95]
	ds_read_b128 v[244:247], v217
	ds_read_b128 v[248:251], v217 offset:8192
	v_add_f32_e32 v219, v69, v219
	v_cvt_pk_bf16_f32 v69, v74, v75
	v_add_f32_e32 v219, v70, v219
	v_cvt_pk_bf16_f32 v70, v76, v77
	s_waitcnt lgkmcnt(3)
	v_mfma_f32_32x32x16_bf16 v[96:111], v[236:239], v[140:143], v[96:111]
	v_add_f32_e32 v219, v71, v219
	v_cvt_pk_bf16_f32 v71, v78, v79
	v_add_f32_e32 v219, v72, v219
	v_add_f32_e32 v219, v73, v219
	s_waitcnt lgkmcnt(2)
	v_mfma_f32_32x32x16_bf16 v[80:95], v[240:243], v[140:143], v[80:95]
	ds_read_b128 v[236:239], v218
	ds_read_b128 v[240:243], v218 offset:8192
	v_permlane32_swap_b32_e32 v64, v66
	v_add_f32_e32 v219, v74, v219
	s_waitcnt lgkmcnt(3)
	v_mfma_f32_32x32x16_bf16 v[96:111], v[244:247], v[128:131], v[96:111]
	v_permlane32_swap_b32_e32 v65, v67
	v_add_f32_e32 v219, v75, v219
	v_permlane32_swap_b32_e32 v68, v70
	s_waitcnt lgkmcnt(2)
	v_mfma_f32_32x32x16_bf16 v[80:95], v[248:251], v[128:131], v[80:95]
	ds_read_b64_tr_b16 v[244:245], v206 offset:0
	ds_read_b64_tr_b16 v[246:247], v206 offset:2048
	ds_read_b64_tr_b16 v[248:249], v206 offset:4096
	ds_read_b64_tr_b16 v[250:251], v206 offset:6144
	v_add_f32_e32 v219, v76, v219
	v_permlane32_swap_b32_e32 v69, v71
	v_add_f32_e32 v219, v77, v219
	s_waitcnt lgkmcnt(5)
	v_mfma_f32_32x32x16_bf16 v[96:111], v[236:239], v[136:139], v[96:111]
	v_add_f32_e32 v219, v78, v219
	v_add_f32_e32 v219, v79, v219
	v_mov_b32_e32 v220, v219
	s_nop 1
	s_waitcnt lgkmcnt(4)
	v_mfma_f32_32x32x16_bf16 v[80:95], v[240:243], v[136:139], v[80:95]
	v_permlane32_swap_b32_e32 v219, v220
	v_add_f32_e32 v219, v219, v220
	v_add_f32_e32 v204, v204, v219
	ds_read_b64_tr_b16 v[236:237], v206 offset:8192
	ds_read_b64_tr_b16 v[238:239], v206 offset:10240
	ds_read_b64_tr_b16 v[240:241], v206 offset:12288
	ds_read_b64_tr_b16 v[242:243], v206 offset:14336
	s_and_b64 vcc, exec, s[6:7]
	s_cbranch_vccnz .Lat4_noshift_A
	s_nop 15
	v_pk_add_f32 v[110:111], v[182:183], v[110:111]
	v_pk_add_f32 v[108:109], v[182:183], v[108:109]
	v_pk_add_f32 v[106:107], v[182:183], v[106:107]
	v_pk_add_f32 v[104:105], v[182:183], v[104:105]
	v_pk_add_f32 v[102:103], v[182:183], v[102:103]
	v_pk_add_f32 v[100:101], v[182:183], v[100:101]
	v_pk_add_f32 v[98:99], v[182:183], v[98:99]
	v_pk_add_f32 v[96:97], v[182:183], v[96:97]
	v_pk_add_f32 v[94:95], v[182:183], v[94:95]
	v_pk_add_f32 v[92:93], v[182:183], v[92:93]
	v_pk_add_f32 v[90:91], v[182:183], v[90:91]
	v_pk_add_f32 v[88:89], v[182:183], v[88:89]
	v_pk_add_f32 v[86:87], v[182:183], v[86:87]
	v_pk_add_f32 v[84:85], v[182:183], v[84:85]
	v_pk_add_f32 v[82:83], v[182:183], v[82:83]
	v_pk_add_f32 v[80:81], v[182:183], v[80:81]
.Lat4_noshift_A:
	s_waitcnt lgkmcnt(6)
	v_mfma_f32_32x32x16_bf16 v[0:15], v[160:163], v[244:247], v[0:15]
	ds_read_b64_tr_b16 v[244:245], v206 offset:512
	ds_read_b64_tr_b16 v[246:247], v206 offset:2560
	s_waitcnt lgkmcnt(6)
	v_mfma_f32_32x32x16_bf16 v[0:15], v[164:167], v[248:251], v[0:15]
	ds_read_b64_tr_b16 v[248:249], v206 offset:4608
	ds_read_b64_tr_b16 v[250:251], v206 offset:6656
	s_waitcnt vmcnt(0)
	ds_write_b128 v209, v[148:151]
	v_exp_f32_e32 v181, v96
	v_exp_f32_e32 v221, v97
	s_waitcnt lgkmcnt(7)
	v_mfma_f32_32x32x16_bf16 v[0:15], v[64:67], v[236:239], v[0:15]
	ds_read_b64_tr_b16 v[236:237], v206 offset:8704
	ds_read_b64_tr_b16 v[238:239], v206 offset:10752
	ds_write_b128 v210, v[152:155]
	v_exp_f32_e32 v222, v98
	v_exp_f32_e32 v223, v99
	s_waitcnt lgkmcnt(8)
	v_mfma_f32_32x32x16_bf16 v[0:15], v[68:71], v[240:243], v[0:15]
	ds_read_b64_tr_b16 v[240:241], v206 offset:12800
	ds_read_b64_tr_b16 v[242:243], v206 offset:14848
	ds_write_b128 v252, v[144:147] offset:16384
	v_exp_f32_e32 v224, v100
	v_exp_f32_e32 v225, v101
	s_waitcnt lgkmcnt(9)
	v_mfma_f32_32x32x16_bf16 v[16:31], v[160:163], v[244:247], v[16:31]
	ds_read_b64_tr_b16 v[244:245], v206 offset:1024
	ds_read_b64_tr_b16 v[246:247], v206 offset:3072
	ds_write_b128 v253, v[156:159] offset:16384
	v_exp_f32_e32 v226, v102
	v_exp_f32_e32 v227, v103
	s_waitcnt lgkmcnt(10)
	v_mfma_f32_32x32x16_bf16 v[16:31], v[164:167], v[248:251], v[16:31]
	ds_read_b64_tr_b16 v[248:249], v206 offset:5120
	ds_read_b64_tr_b16 v[250:251], v206 offset:7168
	v_exp_f32_e32 v228, v104
	v_exp_f32_e32 v229, v105
	s_waitcnt lgkmcnt(9)
	v_mfma_f32_32x32x16_bf16 v[16:31], v[64:67], v[236:239], v[16:31]
	ds_read_b64_tr_b16 v[236:237], v206 offset:9216
	ds_read_b64_tr_b16 v[238:239], v206 offset:11264
	v_lshl_add_u64 v[144:145], v[190:191], 0, s[98:99]
	global_load_dwordx4 v[156:159], v[190:191], off
	global_load_dwordx4 v[144:147], v[144:145], off
	v_exp_f32_e32 v230, v106
	v_exp_f32_e32 v231, v107
	s_waitcnt lgkmcnt(8)
; #define SBAR() __builtin_amdgcn_sched_barrier(0)
; #define SLOAD(i, k0) do { sr_[i].vs0 = LD8(&Vh[(long)((k0) + sr) * LDK + sc]); sr_[i].vs1 = LD8(&Vh[(long)((k0) + 32 + sr) * LDK + sc]); \
;     sr_[i].ks0 = LD8(&Kh[(long)((k0) + sr) * LDK + sc]); sr_[i].ks1 = LD8(&Kh[(long)((k0) + 32 + sr) * LDK + sc]); } while (0)
; #define SWRITE(b, i) do { *(bf16x8*)((char*)V_lds + (b) * SHM_V + vst0) = sr_[i].vs0;          \
;     *(bf16x8*)((char*)V_lds + (b) * SHM_V + vst1) = sr_[i].vs1; int kc = sc * 2;               \
;     *(bf16x8*)((char*)K_lds + (b) * SHM_K + KSWZ(sr, kc)) = sr_[i].ks0;                       \
;     *(bf16x8*)((char*)K_lds + (b) * SHM_K + KSWZ(32 + sr, kc)) = sr_[i].ks1; } while (0)
; #define SWAIT() asm volatile("s_waitcnt vmcnt(4)" ::: "memory")
; __device__ __forceinline__ void attn_body(const bf16_t* __restrict__ Qb, const bf16_t* __restrict__ Kh, const bf16_t* __restrict__ Vh, const bf16_t* __restrict__ Zb, ...
;     ...
;         SBAR(); qkt(pB0, pB1, (bf16_t*)((char*)K_lds + SHM_K), qr, r32, hi);
;         finishSM(pA0, pA1, 1.f, l_reg, pa0, pa1, pa2, pa3); SBAR();
;         SLOAD(SO, (j + 2) * KVBLK); SBAR();
;         pv_d0(o, vb0, pa0, pa1, pa2, pa3); partialSM(pB0, pB1, negBC);
;         __syncthreads(); SWAIT(); SWRITE(0, SE);
;         __syncthreads();
;         SBAR(); qkt(pA0, pA1, K_lds, qr, r32, hi);
;         finishSM(pB0, pB1, 1.f, l_reg, pa0, pa1, pa2, pa3); SBAR();
;         SLOAD(SE, ((j + 3 < NT) ? (j + 3) : (NT - 1)) * KVBLK); SBAR();
;         pv_d0(o, vb0 + (int)SHM_V, pa0, pa1, pa2, pa3); partialSM(pA0, pA1, negBC);
;         __syncthreads(); SWAIT(); SWRITE(1, SO);
;         __syncthreads();
	v_mfma_f32_32x32x16_bf16 v[16:31], v[68:71], v[240:243], v[16:31]
	ds_read_b64_tr_b16 v[240:241], v206 offset:13312
	ds_read_b64_tr_b16 v[242:243], v206 offset:15360
	v_exp_f32_e32 v232, v108
	v_exp_f32_e32 v233, v109
	s_waitcnt lgkmcnt(7)
	v_mfma_f32_32x32x16_bf16 v[32:47], v[160:163], v[244:247], v[32:47]
	ds_read_b64_tr_b16 v[244:245], v206 offset:1536
	ds_read_b64_tr_b16 v[246:247], v206 offset:3584
	v_lshl_add_u64 v[190:191], v[190:191], 0, s[100:101]
	v_lshl_add_u64 v[152:153], v[190:191], 0, s[100:101]
	v_lshl_add_u64 v[148:149], v[152:153], 0, s[98:99]
	global_load_dwordx4 v[152:155], v[152:153], off offset:-512
	global_load_dwordx4 v[148:151], v[148:149], off offset:-512
	v_exp_f32_e32 v234, v110
	v_exp_f32_e32 v235, v111
	s_waitcnt lgkmcnt(6)
	v_mfma_f32_32x32x16_bf16 v[32:47], v[164:167], v[248:251], v[32:47]
	ds_read_b64_tr_b16 v[248:249], v206 offset:5632
	ds_read_b64_tr_b16 v[250:251], v206 offset:7680
	v_exp_f32_e32 v80, v80
	v_exp_f32_e32 v81, v81
	s_waitcnt lgkmcnt(6)
	v_mfma_f32_32x32x16_bf16 v[32:47], v[64:67], v[236:239], v[32:47]
	ds_read_b64_tr_b16 v[236:237], v206 offset:9728
	ds_read_b64_tr_b16 v[238:239], v206 offset:11776
	s_lshl_b32 s15, 0x4000, s14
	s_cmp_eq_u32 s14, 2
	s_cselect_b32 s15, 0xffff4000, s15
	s_add_i32 s40, s14, -1
	s_cmp_eq_u32 s14, 0
	s_cselect_b32 s40, 2, s40
	s_lshl_b32 s35, 0x4000, s40
	s_cmp_eq_u32 s40, 2
	s_cselect_b32 s35, 0xffff4000, s35
	s_add_i32 s40, s14, 1
	s_cmp_eq_u32 s14, 2
	s_cselect_b32 s14, 0, s40
	v_add_u32_e32 v211, s15, v211
	v_add_u32_e32 v212, s15, v212
	v_add_u32_e32 v213, s15, v213
	v_add_u32_e32 v214, s15, v214
	v_add_u32_e32 v215, s15, v215
	v_add_u32_e32 v216, s15, v216
	v_add_u32_e32 v217, s15, v217
	v_add_u32_e32 v218, s15, v218
	v_add_u32_e32 v209, s35, v209
	v_add_u32_e32 v210, s35, v210
	v_exp_f32_e32 v82, v82
	v_exp_f32_e32 v83, v83
	s_waitcnt lgkmcnt(6)
	v_mfma_f32_32x32x16_bf16 v[32:47], v[68:71], v[240:243], v[32:47]
	ds_read_b64_tr_b16 v[240:241], v206 offset:13824
	ds_read_b64_tr_b16 v[242:243], v206 offset:15872
	v_exp_f32_e32 v84, v84
	v_exp_f32_e32 v85, v85
	s_waitcnt lgkmcnt(6)
	v_mfma_f32_32x32x16_bf16 v[48:63], v[160:163], v[244:247], v[48:63]
	v_exp_f32_e32 v86, v86
	v_exp_f32_e32 v87, v87
	s_waitcnt lgkmcnt(4)
	v_mfma_f32_32x32x16_bf16 v[48:63], v[164:167], v[248:251], v[48:63]
	v_exp_f32_e32 v88, v88
	v_exp_f32_e32 v89, v89
	v_exp_f32_e32 v90, v90
	s_waitcnt lgkmcnt(2)
	v_mfma_f32_32x32x16_bf16 v[48:63], v[64:67], v[236:239], v[48:63]
	v_exp_f32_e32 v91, v91
	v_exp_f32_e32 v92, v92
	v_exp_f32_e32 v93, v93
	s_waitcnt lgkmcnt(0)
	v_mfma_f32_32x32x16_bf16 v[48:63], v[68:71], v[240:243], v[48:63]
	v_exp_f32_e32 v94, v94
	v_exp_f32_e32 v95, v95
	v_mov_b32_e32 v252, v207
	v_mov_b32_e32 v253, v208
	ds_read_b128 v[168:171], v211
	ds_read_b128 v[172:175], v211 offset:8192
	s_nop 0
	s_barrier
	ds_read_b128 v[236:239], v212
	ds_read_b128 v[240:243], v212 offset:8192
	ds_read_b128 v[244:247], v213
	ds_read_b128 v[248:251], v213 offset:8192
	v_add_f32_e32 v219, v181, v221
	v_cvt_pk_bf16_f32 v160, v181, v221
	s_waitcnt lgkmcnt(5)
	v_mfma_f32_32x32x16_bf16 v[96:111], v[168:171], v[116:119], 0
	v_add_f32_e32 v219, v222, v219
	v_cvt_pk_bf16_f32 v161, v222, v223
	v_add_f32_e32 v219, v223, v219
	v_cvt_pk_bf16_f32 v162, v224, v225
	v_add_f32_e32 v219, v224, v219
	s_waitcnt lgkmcnt(4)
	v_mfma_f32_32x32x16_bf16 v[64:79], v[172:175], v[116:119], 0
	v_cvt_pk_bf16_f32 v163, v226, v227
	v_add_f32_e32 v219, v225, v219
	v_cvt_pk_bf16_f32 v164, v228, v229
	v_add_f32_e32 v219, v226, v219
	v_cvt_pk_bf16_f32 v165, v230, v231
	s_waitcnt lgkmcnt(3)
	v_mfma_f32_32x32x16_bf16 v[96:111], v[236:239], v[124:127], v[96:111]
	v_add_f32_e32 v219, v227, v219
	v_cvt_pk_bf16_f32 v166, v232, v233
	v_add_f32_e32 v219, v228, v219
	v_cvt_pk_bf16_f32 v167, v234, v235
	v_add_f32_e32 v219, v229, v219
	s_waitcnt lgkmcnt(2)
	v_mfma_f32_32x32x16_bf16 v[64:79], v[240:243], v[124:127], v[64:79]
	ds_read_b128 v[236:239], v214
	ds_read_b128 v[240:243], v214 offset:8192
	v_permlane32_swap_b32_e32 v160, v162
	v_add_f32_e32 v219, v230, v219
	s_waitcnt lgkmcnt(3)
	v_mfma_f32_32x32x16_bf16 v[96:111], v[244:247], v[112:115], v[96:111]
	v_permlane32_swap_b32_e32 v161, v163
	v_add_f32_e32 v219, v231, v219
	v_permlane32_swap_b32_e32 v164, v166
	s_waitcnt lgkmcnt(2)
	v_mfma_f32_32x32x16_bf16 v[64:79], v[248:251], v[112:115], v[64:79]
	ds_read_b128 v[244:247], v215
	ds_read_b128 v[248:251], v215 offset:8192
	v_add_f32_e32 v219, v232, v219
	v_permlane32_swap_b32_e32 v165, v167
	v_add_f32_e32 v219, v233, v219
	s_waitcnt lgkmcnt(3)
	v_mfma_f32_32x32x16_bf16 v[96:111], v[236:239], v[120:123], v[96:111]
	v_add_f32_e32 v219, v234, v219
	v_add_f32_e32 v219, v235, v219
	v_add_f32_e32 v219, v80, v219
	v_cvt_pk_bf16_f32 v80, v80, v81
	s_waitcnt lgkmcnt(2)
	v_mfma_f32_32x32x16_bf16 v[64:79], v[240:243], v[120:123], v[64:79]
	ds_read_b128 v[236:239], v216
	ds_read_b128 v[240:243], v216 offset:8192
	v_add_f32_e32 v219, v81, v219
	v_cvt_pk_bf16_f32 v81, v82, v83
	v_add_f32_e32 v219, v82, v219
	v_cvt_pk_bf16_f32 v82, v84, v85
	s_waitcnt lgkmcnt(3)
	v_mfma_f32_32x32x16_bf16 v[96:111], v[244:247], v[132:135], v[96:111]
	v_add_f32_e32 v219, v83, v219
	v_cvt_pk_bf16_f32 v83, v86, v87
	v_add_f32_e32 v219, v84, v219
	v_cvt_pk_bf16_f32 v84, v88, v89
	s_waitcnt lgkmcnt(2)
	v_mfma_f32_32x32x16_bf16 v[64:79], v[248:251], v[132:135], v[64:79]
	ds_read_b128 v[244:247], v217
	ds_read_b128 v[248:251], v217 offset:8192
	v_add_f32_e32 v219, v85, v219
	v_cvt_pk_bf16_f32 v85, v90, v91
	v_add_f32_e32 v219, v86, v219
	v_cvt_pk_bf16_f32 v86, v92, v93
	s_waitcnt lgkmcnt(3)
; #define SBAR() __builtin_amdgcn_sched_barrier(0)
; #define SLOAD(i, k0) do { sr_[i].vs0 = LD8(&Vh[(long)((k0) + sr) * LDK + sc]); sr_[i].vs1 = LD8(&Vh[(long)((k0) + 32 + sr) * LDK + sc]); \
;     sr_[i].ks0 = LD8(&Kh[(long)((k0) + sr) * LDK + sc]); sr_[i].ks1 = LD8(&Kh[(long)((k0) + 32 + sr) * LDK + sc]); } while (0)
; #define SWRITE(b, i) do { *(bf16x8*)((char*)V_lds + (b) * SHM_V + vst0) = sr_[i].vs0;          \
;     *(bf16x8*)((char*)V_lds + (b) * SHM_V + vst1) = sr_[i].vs1; int kc = sc * 2;               \
;     *(bf16x8*)((char*)K_lds + (b) * SHM_K + KSWZ(sr, kc)) = sr_[i].ks0;                       \
;     *(bf16x8*)((char*)K_lds + (b) * SHM_K + KSWZ(32 + sr, kc)) = sr_[i].ks1; } while (0)
; #define SWAIT() asm volatile("s_waitcnt vmcnt(4)" ::: "memory")
; __device__ __forceinline__ void finishSM(f32x16& p0, f32x16& p1, float alpha, float& l_reg, bf16x8& pa0, bf16x8& pa1, bf16x8& pa2, bf16x8& pa3) {
;     for (int r = 0; r < 16; ++r) p1[r] = __builtin_amdgcn_exp2f(p1[r]);
;     float ps = 0; for (int r = 0; r < 16; ++r) ps += p0[r]; for (int r = 0; r < 16; ++r) ps += p1[r];
;     { auto rr = __builtin_amdgcn_permlane32_swap(__float_as_uint(ps), __float_as_uint(ps), false, false);
;       ps = __uint_as_float(rr[0]) + __uint_as_float(rr[1]); }
;     l_reg = l_reg * alpha + ps;
;     ...
;     PK4(p0, 0, pa0); PK4(p0, 8, pa1); PK4(p1, 0, pa2); PK4(p1, 8, pa3);
;     ...
; }
; __device__ __forceinline__ void attn_body(const bf16_t* __restrict__ Qb, const bf16_t* __restrict__ Kh, const bf16_t* __restrict__ Vh, const bf16_t* __restrict__ Zb, ...
;     ...
;         SBAR(); qkt(pA0, pA1, K_lds, qr, r32, hi);
;         finishSM(pB0, pB1, 1.f, l_reg, pa0, pa1, pa2, pa3); SBAR();
;         SLOAD(SE, ((j + 3 < NT) ? (j + 3) : (NT - 1)) * KVBLK); SBAR();
;         pv_d0(o, vb0 + (int)SHM_V, pa0, pa1, pa2, pa3); partialSM(pA0, pA1, negBC);
;         __syncthreads(); SWAIT(); SWRITE(1, SO);
	v_mfma_f32_32x32x16_bf16 v[96:111], v[236:239], v[140:143], v[96:111]
	v_add_f32_e32 v219, v87, v219
	v_cvt_pk_bf16_f32 v87, v94, v95
	v_add_f32_e32 v219, v88, v219
	v_add_f32_e32 v219, v89, v219
	s_waitcnt lgkmcnt(2)
	v_mfma_f32_32x32x16_bf16 v[64:79], v[240:243], v[140:143], v[64:79]
	ds_read_b128 v[236:239], v218
	ds_read_b128 v[240:243], v218 offset:8192
	v_permlane32_swap_b32_e32 v80, v82
	v_add_f32_e32 v219, v90, v219
	s_waitcnt lgkmcnt(3)
	v_mfma_f32_32x32x16_bf16 v[96:111], v[244:247], v[128:131], v[96:111]
	v_permlane32_swap_b32_e32 v81, v83
	v_add_f32_e32 v219, v91, v219
	v_permlane32_swap_b32_e32 v84, v86
	s_waitcnt lgkmcnt(2)
	v_mfma_f32_32x32x16_bf16 v[64:79], v[248:251], v[128:131], v[64:79]
	ds_read_b64_tr_b16 v[244:245], v205 offset:0
	ds_read_b64_tr_b16 v[246:247], v205 offset:2048
	ds_read_b64_tr_b16 v[248:249], v205 offset:4096
	ds_read_b64_tr_b16 v[250:251], v205 offset:6144
	v_add_f32_e32 v219, v92, v219
	v_permlane32_swap_b32_e32 v85, v87
	v_add_f32_e32 v219, v93, v219
	s_waitcnt lgkmcnt(5)
	v_mfma_f32_32x32x16_bf16 v[96:111], v[236:239], v[136:139], v[96:111]
	v_add_f32_e32 v219, v94, v219
	v_add_f32_e32 v219, v95, v219
	v_mov_b32_e32 v220, v219
	s_nop 1
	s_waitcnt lgkmcnt(4)
	v_mfma_f32_32x32x16_bf16 v[64:79], v[240:243], v[136:139], v[64:79]
	v_permlane32_swap_b32_e32 v219, v220
	v_add_f32_e32 v219, v219, v220
	v_add_f32_e32 v204, v204, v219
	ds_read_b64_tr_b16 v[236:237], v205 offset:8192
	ds_read_b64_tr_b16 v[238:239], v205 offset:10240
	ds_read_b64_tr_b16 v[240:241], v205 offset:12288
	ds_read_b64_tr_b16 v[242:243], v205 offset:14336
	s_and_b64 vcc, exec, s[6:7]
	s_cbranch_vccnz .Lat4_noshift_B
	s_nop 15
	v_pk_add_f32 v[110:111], v[182:183], v[110:111]
	v_pk_add_f32 v[108:109], v[182:183], v[108:109]
	v_pk_add_f32 v[106:107], v[182:183], v[106:107]
	v_pk_add_f32 v[104:105], v[182:183], v[104:105]
	v_pk_add_f32 v[102:103], v[182:183], v[102:103]
	v_pk_add_f32 v[100:101], v[182:183], v[100:101]
	v_pk_add_f32 v[98:99], v[182:183], v[98:99]
	v_pk_add_f32 v[96:97], v[182:183], v[96:97]
	v_pk_add_f32 v[78:79], v[182:183], v[78:79]
	v_pk_add_f32 v[76:77], v[182:183], v[76:77]
	v_pk_add_f32 v[74:75], v[182:183], v[74:75]
	v_pk_add_f32 v[72:73], v[182:183], v[72:73]
	v_pk_add_f32 v[70:71], v[182:183], v[70:71]
	v_pk_add_f32 v[68:69], v[182:183], v[68:69]
	v_pk_add_f32 v[66:67], v[182:183], v[66:67]
	v_pk_add_f32 v[64:65], v[182:183], v[64:65]
; #define SBAR() __builtin_amdgcn_sched_barrier(0)
; #define SLOAD(i, k0) do { sr_[i].vs0 = LD8(&Vh[(long)((k0) + sr) * LDK + sc]); sr_[i].vs1 = LD8(&Vh[(long)((k0) + 32 + sr) * LDK + sc]); \
;     sr_[i].ks0 = LD8(&Kh[(long)((k0) + sr) * LDK + sc]); sr_[i].ks1 = LD8(&Kh[(long)((k0) + 32 + sr) * LDK + sc]); } while (0)
; #define SWRITE(b, i) do { *(bf16x8*)((char*)V_lds + (b) * SHM_V + vst0) = sr_[i].vs0;          \
;     *(bf16x8*)((char*)V_lds + (b) * SHM_V + vst1) = sr_[i].vs1; int kc = sc * 2;               \
;     *(bf16x8*)((char*)K_lds + (b) * SHM_K + KSWZ(sr, kc)) = sr_[i].ks0;                       \
;     *(bf16x8*)((char*)K_lds + (b) * SHM_K + KSWZ(32 + sr, kc)) = sr_[i].ks1; } while (0)
; #define SWAIT() asm volatile("s_waitcnt vmcnt(4)" ::: "memory")
; __device__ __forceinline__ void attn_body(const bf16_t* __restrict__ Qb, const bf16_t* __restrict__ Kh, const bf16_t* __restrict__ Vh, const bf16_t* __restrict__ Zb, ...
;     ...
;         SBAR(); qkt(pB0, pB1, (bf16_t*)((char*)K_lds + SHM_K), qr, r32, hi);
;         finishSM(pA0, pA1, 1.f, l_reg, pa0, pa1, pa2, pa3); SBAR();
;         SLOAD(SO, (j + 2) * KVBLK); SBAR();
;         pv_d0(o, vb0, pa0, pa1, pa2, pa3); partialSM(pB0, pB1, negBC);
;         __syncthreads(); SWAIT(); SWRITE(0, SE);
;         __syncthreads();
;         SBAR(); qkt(pA0, pA1, K_lds, qr, r32, hi);
;         finishSM(pB0, pB1, 1.f, l_reg, pa0, pa1, pa2, pa3); SBAR();
;         SLOAD(SE, ((j + 3 < NT) ? (j + 3) : (NT - 1)) * KVBLK); SBAR();
;         pv_d0(o, vb0 + (int)SHM_V, pa0, pa1, pa2, pa3); partialSM(pA0, pA1, negBC);
;         __syncthreads(); SWAIT(); SWRITE(1, SO);
;         __syncthreads();
.Lat4_noshift_B:
	s_waitcnt lgkmcnt(6)
	v_mfma_f32_32x32x16_bf16 v[0:15], v[160:163], v[244:247], v[0:15]
	ds_read_b64_tr_b16 v[244:245], v205 offset:512
	ds_read_b64_tr_b16 v[246:247], v205 offset:2560
	s_waitcnt lgkmcnt(6)
	v_mfma_f32_32x32x16_bf16 v[0:15], v[164:167], v[248:251], v[0:15]
	ds_read_b64_tr_b16 v[248:249], v205 offset:4608
	ds_read_b64_tr_b16 v[250:251], v205 offset:6656
	s_waitcnt vmcnt(0)
	ds_write_b128 v209, v[148:151]
	v_exp_f32_e32 v233, v96
	v_exp_f32_e32 v235, v97
	s_waitcnt lgkmcnt(7)
	v_mfma_f32_32x32x16_bf16 v[0:15], v[80:83], v[236:239], v[0:15]
	ds_read_b64_tr_b16 v[236:237], v205 offset:8704
	ds_read_b64_tr_b16 v[238:239], v205 offset:10752
	ds_write_b128 v210, v[152:155]
	v_exp_f32_e32 v231, v98
	v_exp_f32_e32 v234, v99
	s_waitcnt lgkmcnt(8)
	v_mfma_f32_32x32x16_bf16 v[0:15], v[84:87], v[240:243], v[0:15]
	ds_read_b64_tr_b16 v[240:241], v205 offset:12800
	ds_read_b64_tr_b16 v[242:243], v205 offset:14848
	ds_write_b128 v207, v[144:147] offset:0
	v_exp_f32_e32 v230, v100
	v_exp_f32_e32 v232, v101
	s_waitcnt lgkmcnt(9)
	v_mfma_f32_32x32x16_bf16 v[16:31], v[160:163], v[244:247], v[16:31]
	ds_read_b64_tr_b16 v[244:245], v205 offset:1024
	ds_read_b64_tr_b16 v[246:247], v205 offset:3072
	ds_write_b128 v208, v[156:159] offset:0
	v_exp_f32_e32 v228, v102
	v_exp_f32_e32 v229, v103
	s_waitcnt lgkmcnt(10)
	v_mfma_f32_32x32x16_bf16 v[16:31], v[164:167], v[248:251], v[16:31]
	ds_read_b64_tr_b16 v[248:249], v205 offset:5120
	ds_read_b64_tr_b16 v[250:251], v205 offset:7168
	v_exp_f32_e32 v225, v104
	v_exp_f32_e32 v227, v105
	s_waitcnt lgkmcnt(9)
	v_mfma_f32_32x32x16_bf16 v[16:31], v[80:83], v[236:239], v[16:31]
	ds_read_b64_tr_b16 v[236:237], v205 offset:9216
	ds_read_b64_tr_b16 v[238:239], v205 offset:11264
	v_lshl_add_u64 v[144:145], v[190:191], 0, s[98:99]
	global_load_dwordx4 v[156:159], v[190:191], off
	global_load_dwordx4 v[144:147], v[144:145], off
	v_exp_f32_e32 v224, v106
	v_exp_f32_e32 v226, v107
	s_waitcnt lgkmcnt(8)
	v_mfma_f32_32x32x16_bf16 v[16:31], v[84:87], v[240:243], v[16:31]
	ds_read_b64_tr_b16 v[240:241], v205 offset:13312
	ds_read_b64_tr_b16 v[242:243], v205 offset:15360
	v_exp_f32_e32 v221, v108
	v_exp_f32_e32 v223, v109
	s_waitcnt lgkmcnt(7)
	v_mfma_f32_32x32x16_bf16 v[32:47], v[160:163], v[244:247], v[32:47]
	ds_read_b64_tr_b16 v[244:245], v205 offset:1536
	ds_read_b64_tr_b16 v[246:247], v205 offset:3584
	v_lshl_add_u64 v[190:191], v[190:191], 0, s[100:101]
	v_lshl_add_u64 v[152:153], v[190:191], 0, s[100:101]
	v_lshl_add_u64 v[148:149], v[152:153], 0, s[98:99]
	global_load_dwordx4 v[152:155], v[152:153], off offset:-512
	global_load_dwordx4 v[148:151], v[148:149], off offset:-512
	v_exp_f32_e32 v181, v110
	v_exp_f32_e32 v222, v111
	s_waitcnt lgkmcnt(6)
	v_mfma_f32_32x32x16_bf16 v[32:47], v[164:167], v[248:251], v[32:47]
	ds_read_b64_tr_b16 v[248:249], v205 offset:5632
	ds_read_b64_tr_b16 v[250:251], v205 offset:7680
	v_exp_f32_e32 v64, v64
	v_exp_f32_e32 v65, v65
	s_waitcnt lgkmcnt(6)
	v_mfma_f32_32x32x16_bf16 v[32:47], v[80:83], v[236:239], v[32:47]
	ds_read_b64_tr_b16 v[236:237], v205 offset:9728
	ds_read_b64_tr_b16 v[238:239], v205 offset:11776
	s_lshl_b32 s15, 0x4000, s14
	s_cmp_eq_u32 s14, 2
	s_cselect_b32 s15, 0xffff4000, s15
	s_add_i32 s40, s14, -1
	s_cmp_eq_u32 s14, 0
	s_cselect_b32 s40, 2, s40
	s_lshl_b32 s35, 0x4000, s40
	s_cmp_eq_u32 s40, 2
	s_cselect_b32 s35, 0xffff4000, s35
	s_add_i32 s40, s14, 1
	s_cmp_eq_u32 s14, 2
	s_cselect_b32 s14, 0, s40
	v_add_u32_e32 v211, s15, v211
	v_add_u32_e32 v212, s15, v212
	v_add_u32_e32 v213, s15, v213
	v_add_u32_e32 v214, s15, v214
	v_add_u32_e32 v215, s15, v215
	v_add_u32_e32 v216, s15, v216
	v_add_u32_e32 v217, s15, v217
	v_add_u32_e32 v218, s15, v218
	v_add_u32_e32 v209, s35, v209
	v_add_u32_e32 v210, s35, v210
	v_exp_f32_e32 v66, v66
	v_exp_f32_e32 v67, v67
	s_waitcnt lgkmcnt(6)
	v_mfma_f32_32x32x16_bf16 v[32:47], v[84:87], v[240:243], v[32:47]
	ds_read_b64_tr_b16 v[240:241], v205 offset:13824
	ds_read_b64_tr_b16 v[242:243], v205 offset:15872
	v_exp_f32_e32 v68, v68
	v_exp_f32_e32 v69, v69
	s_waitcnt lgkmcnt(6)
	v_mfma_f32_32x32x16_bf16 v[48:63], v[160:163], v[244:247], v[48:63]
	v_exp_f32_e32 v70, v70
	v_exp_f32_e32 v71, v71
	s_waitcnt lgkmcnt(4)
	v_mfma_f32_32x32x16_bf16 v[48:63], v[164:167], v[248:251], v[48:63]
	v_exp_f32_e32 v72, v72
	v_exp_f32_e32 v73, v73
	v_exp_f32_e32 v74, v74
	s_waitcnt lgkmcnt(2)
	v_mfma_f32_32x32x16_bf16 v[48:63], v[80:83], v[236:239], v[48:63]
	v_exp_f32_e32 v75, v75
	v_exp_f32_e32 v76, v76
	v_exp_f32_e32 v77, v77
	s_waitcnt lgkmcnt(0)
	v_mfma_f32_32x32x16_bf16 v[48:63], v[84:87], v[240:243], v[48:63]
	v_exp_f32_e32 v78, v78
	v_exp_f32_e32 v79, v79
	ds_read_b128 v[168:171], v211
	ds_read_b128 v[172:175], v211 offset:8192
	s_nop 0
	s_add_i32 s22, s39, 2
	s_cmp_ge_u32 s39, s33
	s_barrier
	s_cbranch_scc1 .Lat4_tail
	s_mov_b32 s39, s22
	s_branch .LBB0_490

; #define SBAR() __builtin_amdgcn_sched_barrier(0)
; template <int D0> __device__ __forceinline__ void pv_one(f32x16& od, int vb, bf16x8 pa0, bf16x8 pa1, bf16x8 pa2, bf16x8 pa3) {
;     const s16x4 l0 = tr_read<v_rd_off(D0, 0, 0)>(vb), h0 = tr_read<v_rd_off(D0, 0, 1)>(vb), l1 = tr_read<v_rd_off(D0, 1, 0)>(vb), h1 = tr_read<v_rd_off(D0, 1, 1)>(vb);
;     const s16x4 l2 = tr_read<v_rd_off(D0, 2, 0)>(vb), h2 = tr_read<v_rd_off(D0, 2, 1)>(vb), l3 = tr_read<v_rd_off(D0, 3, 0)>(vb), h3 = tr_read<v_rd_off(D0, 3, 1)>(vb);
;     asm volatile("s_waitcnt lgkmcnt(0)" ::: "memory"); SBAR();
;     ...
;     od = __builtin_amdgcn_mfma_f32_32x32x16_bf16(pa0, PK(l0, h0), od, 0, 0, 0);
;     od = __builtin_amdgcn_mfma_f32_32x32x16_bf16(pa1, PK(l1, h1), od, 0, 0, 0);
;     od = __builtin_amdgcn_mfma_f32_32x32x16_bf16(pa2, PK(l2, h2), od, 0, 0, 0);
;     od = __builtin_amdgcn_mfma_f32_32x32x16_bf16(pa3, PK(l3, h3), od, 0, 0, 0);
;     ...
; }
; __device__ __forceinline__ void pv_d0(f32x16* o, int vb, bf16x8 pa0, bf16x8 pa1, bf16x8 pa2, bf16x8 pa3) {
;     pv_one<0>(o[0], vb, pa0, pa1, pa2, pa3); pv_one<1>(o[1], vb, pa0, pa1, pa2, pa3); pv_one<2>(o[2], vb, pa0, pa1, pa2, pa3); pv_one<3>(o[3], vb, pa0, pa1, pa2, pa3);
; __device__ __forceinline__ void attn_body(const bf16_t* __restrict__ Qb, const bf16_t* __restrict__ Kh, const bf16_t* __restrict__ Vh, const bf16_t* __restrict__ Zb, ...
;     ...
;     SBAR(); qkt(pB0, pB1, (bf16_t*)((char*)K_lds + SHM_K), qr, r32, hi);
;     finishSM(pA0, pA1, 1.f, l_reg, pa0, pa1, pa2, pa3); SBAR();
;     pv_d0(o, vb0, pa0, pa1, pa2, pa3); partialSM(pB0, pB1, negBC);
;     __syncthreads();
.Lat4_noshift_TA:
	s_waitcnt lgkmcnt(6)
	v_mfma_f32_32x32x16_bf16 v[0:15], v[160:163], v[244:247], v[0:15]
	ds_read_b64_tr_b16 v[244:245], v206 offset:512
	ds_read_b64_tr_b16 v[246:247], v206 offset:2560
	s_waitcnt lgkmcnt(6)
	v_mfma_f32_32x32x16_bf16 v[0:15], v[164:167], v[248:251], v[0:15]
	ds_read_b64_tr_b16 v[248:249], v206 offset:4608
	ds_read_b64_tr_b16 v[250:251], v206 offset:6656
	s_waitcnt vmcnt(0)
	ds_write_b128 v207, v[144:147] offset:16384
	v_exp_f32_e32 v181, v96
	v_exp_f32_e32 v221, v97
	s_waitcnt lgkmcnt(7)
	v_mfma_f32_32x32x16_bf16 v[0:15], v[64:67], v[236:239], v[0:15]
	ds_read_b64_tr_b16 v[236:237], v206 offset:8704
	ds_read_b64_tr_b16 v[238:239], v206 offset:10752
	ds_write_b128 v208, v[156:159] offset:16384
	v_exp_f32_e32 v222, v98
	v_exp_f32_e32 v223, v99
	s_waitcnt lgkmcnt(8)
	v_mfma_f32_32x32x16_bf16 v[0:15], v[68:71], v[240:243], v[0:15]
	ds_read_b64_tr_b16 v[240:241], v206 offset:12800
	ds_read_b64_tr_b16 v[242:243], v206 offset:14848
	v_exp_f32_e32 v224, v100
	v_exp_f32_e32 v225, v101
	s_waitcnt lgkmcnt(8)
	v_mfma_f32_32x32x16_bf16 v[16:31], v[160:163], v[244:247], v[16:31]
	ds_read_b64_tr_b16 v[244:245], v206 offset:1024
	ds_read_b64_tr_b16 v[246:247], v206 offset:3072
	v_exp_f32_e32 v226, v102
	v_exp_f32_e32 v227, v103
	s_waitcnt lgkmcnt(8)
	v_mfma_f32_32x32x16_bf16 v[16:31], v[164:167], v[248:251], v[16:31]
	ds_read_b64_tr_b16 v[248:249], v206 offset:5120
	ds_read_b64_tr_b16 v[250:251], v206 offset:7168
	v_exp_f32_e32 v228, v104
	v_exp_f32_e32 v229, v105
	s_waitcnt lgkmcnt(7)
	v_mfma_f32_32x32x16_bf16 v[16:31], v[64:67], v[236:239], v[16:31]
	ds_read_b64_tr_b16 v[236:237], v206 offset:9216
	ds_read_b64_tr_b16 v[238:239], v206 offset:11264
	v_exp_f32_e32 v230, v106
	v_exp_f32_e32 v231, v107
	s_waitcnt lgkmcnt(6)
	v_mfma_f32_32x32x16_bf16 v[16:31], v[68:71], v[240:243], v[16:31]
	ds_read_b64_tr_b16 v[240:241], v206 offset:13312
	ds_read_b64_tr_b16 v[242:243], v206 offset:15360
	v_exp_f32_e32 v232, v108
	v_exp_f32_e32 v233, v109
	s_waitcnt lgkmcnt(6)
	v_mfma_f32_32x32x16_bf16 v[32:47], v[160:163], v[244:247], v[32:47]
	ds_read_b64_tr_b16 v[244:245], v206 offset:1536
	ds_read_b64_tr_b16 v[246:247], v206 offset:3584
	v_exp_f32_e32 v234, v110
	v_exp_f32_e32 v235, v111
	s_waitcnt lgkmcnt(6)
	v_mfma_f32_32x32x16_bf16 v[32:47], v[164:167], v[248:251], v[32:47]
	ds_read_b64_tr_b16 v[248:249], v206 offset:5632
	ds_read_b64_tr_b16 v[250:251], v206 offset:7680
	v_exp_f32_e32 v80, v80
	v_exp_f32_e32 v81, v81
	s_waitcnt lgkmcnt(6)
	v_mfma_f32_32x32x16_bf16 v[32:47], v[64:67], v[236:239], v[32:47]
	ds_read_b64_tr_b16 v[236:237], v206 offset:9728
	ds_read_b64_tr_b16 v[238:239], v206 offset:11776
	v_exp_f32_e32 v82, v82
	v_exp_f32_e32 v83, v83
	s_waitcnt lgkmcnt(6)
	v_mfma_f32_32x32x16_bf16 v[32:47], v[68:71], v[240:243], v[32:47]
	ds_read_b64_tr_b16 v[240:241], v206 offset:13824
	ds_read_b64_tr_b16 v[242:243], v206 offset:15872
	v_exp_f32_e32 v84, v84
	v_exp_f32_e32 v85, v85
	s_waitcnt lgkmcnt(6)
	v_mfma_f32_32x32x16_bf16 v[48:63], v[160:163], v[244:247], v[48:63]
	v_exp_f32_e32 v86, v86
	v_exp_f32_e32 v87, v87
	s_waitcnt lgkmcnt(4)
	v_mfma_f32_32x32x16_bf16 v[48:63], v[164:167], v[248:251], v[48:63]
	v_exp_f32_e32 v88, v88
	v_exp_f32_e32 v89, v89
	v_exp_f32_e32 v90, v90
	s_waitcnt lgkmcnt(2)
	v_mfma_f32_32x32x16_bf16 v[48:63], v[64:67], v[236:239], v[48:63]
	v_exp_f32_e32 v91, v91
	v_exp_f32_e32 v92, v92
	v_exp_f32_e32 v93, v93
	s_waitcnt lgkmcnt(0)
	v_mfma_f32_32x32x16_bf16 v[48:63], v[68:71], v[240:243], v[48:63]
	v_exp_f32_e32 v94, v94
	v_exp_f32_e32 v95, v95
	s_waitcnt lgkmcnt(0)
	s_barrier
; #define SBAR() __builtin_amdgcn_sched_barrier(0)
; __device__ __forceinline__ void finishSM(f32x16& p0, f32x16& p1, float alpha, float& l_reg, bf16x8& pa0, bf16x8& pa1, bf16x8& pa2, bf16x8& pa3) {
;     for (int r = 0; r < 16; ++r) p1[r] = __builtin_amdgcn_exp2f(p1[r]);
;     float ps = 0; for (int r = 0; r < 16; ++r) ps += p0[r]; for (int r = 0; r < 16; ++r) ps += p1[r];
;     { auto rr = __builtin_amdgcn_permlane32_swap(__float_as_uint(ps), __float_as_uint(ps), false, false);
;       ps = __uint_as_float(rr[0]) + __uint_as_float(rr[1]); }
;     l_reg = l_reg * alpha + ps;
;     ...
;     PK4(p0, 0, pa0); PK4(p0, 8, pa1); PK4(p1, 0, pa2); PK4(p1, 8, pa3);
; template <int D0> __device__ __forceinline__ void pv_one(f32x16& od, int vb, bf16x8 pa0, bf16x8 pa1, bf16x8 pa2, bf16x8 pa3) {
;     const s16x4 l0 = tr_read<v_rd_off(D0, 0, 0)>(vb), h0 = tr_read<v_rd_off(D0, 0, 1)>(vb), l1 = tr_read<v_rd_off(D0, 1, 0)>(vb), h1 = tr_read<v_rd_off(D0, 1, 1)>(vb);
;     const s16x4 l2 = tr_read<v_rd_off(D0, 2, 0)>(vb), h2 = tr_read<v_rd_off(D0, 2, 1)>(vb), l3 = tr_read<v_rd_off(D0, 3, 0)>(vb), h3 = tr_read<v_rd_off(D0, 3, 1)>(vb);
;     asm volatile("s_waitcnt lgkmcnt(0)" ::: "memory"); SBAR();
;     ...
;     od = __builtin_amdgcn_mfma_f32_32x32x16_bf16(pa0, PK(l0, h0), od, 0, 0, 0);
;     od = __builtin_amdgcn_mfma_f32_32x32x16_bf16(pa1, PK(l1, h1), od, 0, 0, 0);
;     od = __builtin_amdgcn_mfma_f32_32x32x16_bf16(pa2, PK(l2, h2), od, 0, 0, 0);
;     od = __builtin_amdgcn_mfma_f32_32x32x16_bf16(pa3, PK(l3, h3), od, 0, 0, 0);
;     ...
; }
; __device__ __forceinline__ void pv_d0(f32x16* o, int vb, bf16x8 pa0, bf16x8 pa1, bf16x8 pa2, bf16x8 pa3) {
;     pv_one<0>(o[0], vb, pa0, pa1, pa2, pa3); pv_one<1>(o[1], vb, pa0, pa1, pa2, pa3); pv_one<2>(o[2], vb, pa0, pa1, pa2, pa3); pv_one<3>(o[3], vb, pa0, pa1, pa2, pa3);
	ds_read_b64_tr_b16 v[244:245], v205 offset:0
	ds_read_b64_tr_b16 v[246:247], v205 offset:2048
	ds_read_b64_tr_b16 v[248:249], v205 offset:4096
	ds_read_b64_tr_b16 v[250:251], v205 offset:6144
	ds_read_b64_tr_b16 v[236:237], v205 offset:8192
	ds_read_b64_tr_b16 v[238:239], v205 offset:10240
	ds_read_b64_tr_b16 v[240:241], v205 offset:12288
	ds_read_b64_tr_b16 v[242:243], v205 offset:14336
	v_add_f32_e32 v219, v181, v221
	v_cvt_pk_bf16_f32 v160, v181, v221
	v_add_f32_e32 v219, v222, v219
	v_cvt_pk_bf16_f32 v161, v222, v223
	v_add_f32_e32 v219, v223, v219
	v_cvt_pk_bf16_f32 v162, v224, v225
	v_add_f32_e32 v219, v224, v219
	v_cvt_pk_bf16_f32 v163, v226, v227
	v_add_f32_e32 v219, v225, v219
	v_cvt_pk_bf16_f32 v164, v228, v229
	v_add_f32_e32 v219, v226, v219
	v_cvt_pk_bf16_f32 v165, v230, v231
	v_add_f32_e32 v219, v227, v219
	v_cvt_pk_bf16_f32 v166, v232, v233
	v_add_f32_e32 v219, v228, v219
	v_cvt_pk_bf16_f32 v167, v234, v235
	v_add_f32_e32 v219, v229, v219
	v_permlane32_swap_b32_e32 v160, v162
	v_add_f32_e32 v219, v230, v219
	v_permlane32_swap_b32_e32 v161, v163
	v_add_f32_e32 v219, v231, v219
	v_permlane32_swap_b32_e32 v164, v166
	v_add_f32_e32 v219, v232, v219
	v_permlane32_swap_b32_e32 v165, v167
	v_add_f32_e32 v219, v233, v219
	v_add_f32_e32 v219, v234, v219
	v_add_f32_e32 v219, v235, v219
	v_add_f32_e32 v219, v80, v219
	v_cvt_pk_bf16_f32 v80, v80, v81
	v_add_f32_e32 v219, v81, v219
	v_cvt_pk_bf16_f32 v81, v82, v83
	v_add_f32_e32 v219, v82, v219
	v_cvt_pk_bf16_f32 v82, v84, v85
	v_add_f32_e32 v219, v83, v219
	v_cvt_pk_bf16_f32 v83, v86, v87
	v_add_f32_e32 v219, v84, v219
	v_cvt_pk_bf16_f32 v84, v88, v89
	v_add_f32_e32 v219, v85, v219
	v_cvt_pk_bf16_f32 v85, v90, v91
	v_add_f32_e32 v219, v86, v219
	v_cvt_pk_bf16_f32 v86, v92, v93
	v_add_f32_e32 v219, v87, v219
	v_cvt_pk_bf16_f32 v87, v94, v95
	v_add_f32_e32 v219, v88, v219
	v_add_f32_e32 v219, v89, v219
	v_permlane32_swap_b32_e32 v80, v82
	v_add_f32_e32 v219, v90, v219
	v_permlane32_swap_b32_e32 v81, v83
	v_add_f32_e32 v219, v91, v219
	v_permlane32_swap_b32_e32 v84, v86
	v_add_f32_e32 v219, v92, v219
	v_permlane32_swap_b32_e32 v85, v87
	v_add_f32_e32 v219, v93, v219
	v_add_f32_e32 v219, v94, v219
	v_add_f32_e32 v219, v95, v219
	v_mov_b32_e32 v220, v219
	s_nop 1
	v_permlane32_swap_b32_e32 v219, v220
	v_add_f32_e32 v219, v219, v220
	v_add_f32_e32 v204, v204, v219
	s_waitcnt lgkmcnt(6)
	v_mfma_f32_32x32x16_bf16 v[0:15], v[160:163], v[244:247], v[0:15]
	ds_read_b64_tr_b16 v[244:245], v205 offset:512
	ds_read_b64_tr_b16 v[246:247], v205 offset:2560
	s_waitcnt lgkmcnt(6)
	v_mfma_f32_32x32x16_bf16 v[0:15], v[164:167], v[248:251], v[0:15]
	ds_read_b64_tr_b16 v[248:249], v205 offset:4608
	ds_read_b64_tr_b16 v[250:251], v205 offset:6656
	s_waitcnt lgkmcnt(6)
	v_mfma_f32_32x32x16_bf16 v[0:15], v[80:83], v[236:239], v[0:15]
	ds_read_b64_tr_b16 v[236:237], v205 offset:8704
	ds_read_b64_tr_b16 v[238:239], v205 offset:10752
	s_waitcnt lgkmcnt(6)
	v_mfma_f32_32x32x16_bf16 v[0:15], v[84:87], v[240:243], v[0:15]
	ds_read_b64_tr_b16 v[240:241], v205 offset:12800
	ds_read_b64_tr_b16 v[242:243], v205 offset:14848
	s_waitcnt lgkmcnt(6)
	v_mfma_f32_32x32x16_bf16 v[16:31], v[160:163], v[244:247], v[16:31]
	ds_read_b64_tr_b16 v[244:245], v205 offset:1024
	ds_read_b64_tr_b16 v[246:247], v205 offset:3072
	s_waitcnt lgkmcnt(6)
	v_mfma_f32_32x32x16_bf16 v[16:31], v[164:167], v[248:251], v[16:31]
	ds_read_b64_tr_b16 v[248:249], v205 offset:5120
	ds_read_b64_tr_b16 v[250:251], v205 offset:7168
	s_waitcnt lgkmcnt(6)
	v_mfma_f32_32x32x16_bf16 v[16:31], v[80:83], v[236:239], v[16:31]
	ds_read_b64_tr_b16 v[236:237], v205 offset:9216
	ds_read_b64_tr_b16 v[238:239], v205 offset:11264
	s_waitcnt lgkmcnt(6)
	v_mfma_f32_32x32x16_bf16 v[16:31], v[84:87], v[240:243], v[16:31]
	ds_read_b64_tr_b16 v[240:241], v205 offset:13312
	ds_read_b64_tr_b16 v[242:243], v205 offset:15360
	s_waitcnt lgkmcnt(6)
	v_mfma_f32_32x32x16_bf16 v[32:47], v[160:163], v[244:247], v[32:47]
	ds_read_b64_tr_b16 v[244:245], v205 offset:1536
	ds_read_b64_tr_b16 v[246:247], v205 offset:3584
	s_waitcnt lgkmcnt(6)
	v_mfma_f32_32x32x16_bf16 v[32:47], v[164:167], v[248:251], v[32:47]
	ds_read_b64_tr_b16 v[248:249], v205 offset:5632
	ds_read_b64_tr_b16 v[250:251], v205 offset:7680
	s_waitcnt lgkmcnt(6)
	v_mfma_f32_32x32x16_bf16 v[32:47], v[80:83], v[236:239], v[32:47]
	ds_read_b64_tr_b16 v[236:237], v205 offset:9728
	ds_read_b64_tr_b16 v[238:239], v205 offset:11776
	s_waitcnt lgkmcnt(6)
	v_mfma_f32_32x32x16_bf16 v[32:47], v[84:87], v[240:243], v[32:47]
	ds_read_b64_tr_b16 v[240:241], v205 offset:13824
	ds_read_b64_tr_b16 v[242:243], v205 offset:15872
	s_waitcnt lgkmcnt(6)
	v_mfma_f32_32x32x16_bf16 v[48:63], v[160:163], v[244:247], v[48:63]
	s_waitcnt lgkmcnt(4)
	v_mfma_f32_32x32x16_bf16 v[48:63], v[164:167], v[248:251], v[48:63]
	s_waitcnt lgkmcnt(2)
	v_mfma_f32_32x32x16_bf16 v[48:63], v[80:83], v[236:239], v[48:63]
	s_waitcnt lgkmcnt(0)
	v_mfma_f32_32x32x16_bf16 v[48:63], v[84:87], v[240:243], v[48:63]
	v_mov_b32_e32 v64, 0
	v_mov_b32_e32 v65, 0
	v_mov_b32_e32 v67, 0
	v_mov_b32_e32 v68, 0
	v_and_b32_e32 v66, 0x3fffffc0, v200
	v_lshl_add_u32 v66, v66, 2, s36
	s_setprio 0
	v_cmp_gt_u32_e32 vcc, 32, v203
	s_and_saveexec_b64 s[6:7], vcc
	s_cbranch_execz .LBB0_480
	v_add_f32_e32 v64, v64, v65
	v_add_f32_e32 v64, v204, v64
	v_add_f32_e32 v67, v67, v68
	v_lshl_add_u32 v65, v201, 2, v66
	v_add_f32_e32 v64, v64, v67
	ds_write_b32 v65, v64
	s_branch .LBB0_480
